# mixers A and D: key distance via one shared qpos-ktf per tile and a single v_subrev per score (15 fewer VALU per tile, same bits)
# baseline (speedup 1.0000x reference)
; __device__ __forceinline__ float shx(float v, int mask, int lane) { return __builtin_bit_cast(float, __builtin_amdgcn_ds_bpermute((lane ^ mask) << 2, __builtin_bit_cast(int, v))); }
; template <class BiasF> ...
;     ...
;             const float ktf = (float)(kt + 8 * hi);
;             float tmax = -3.0e38f;
; #pragma unroll
;             for (int r = 0; r < 16; ++r) { sc[r] = sc[r] * c2 + bias.at(r32, kt, ktf + (float)(16 * (r >> 3) + 4 * ((r >> 2) & 1) + (r & 3)), r); tmax = fmaxf(tmax, sc[r]); }
;             tmax = fmaxf(tmax, shx(tmax, 32, lane));
;             if (__any(tmax > m)) { const float mn = fmaxf(m, tmax); const float alpha = __builtin_amdgcn_exp2f(m - mn); m = mn; l *= alpha;
; #pragma unroll
;                 for (int i2 = 0; i2 < 2; ++i2)
; #pragma unroll
;                     for (int r = 0; r < 16; ++r) o[i2][r] *= alpha; }
.LBB0_410:
	s_cmp_ge_u32 s29, s31
	v_cmp_lt_u32_e32 vcc, s29, v84
	s_cselect_b64 s[26:27], -1, 0
	s_or_b64 s[26:27], vcc, s[26:27]
	s_and_b64 vcc, exec, s[26:27]
	s_cbranch_vccnz .LBB0_414
	v_lshl_add_u32 v104, s30, 14, v81
	ds_read_b128 v[34:37], v104
	v_add_u32_e32 v38, s29, v68
	v_cvt_f32_i32_e32 v87, v38
	v_sub_f32_e32 v222, v85, v87
	ds_read_b128 v[92:95], v104 offset:1024
	ds_read_b128 v[96:99], v104 offset:2048
	ds_read_b128 v[100:103], v104 offset:3072
	s_waitcnt lgkmcnt(0)
	v_mfma_f32_32x32x16_bf16 v[34:49], v[34:37], v[50:53], 0
	v_sub_f32_e32 v88, v85, v87
	v_mul_f32_e64 v105, v86, |v88|
	v_subrev_f32_e32 v89, 1.0, v222
	v_cmp_le_f32_e64 vcc, |v88|, s19
	v_mfma_f32_32x32x16_bf16 v[34:49], v[92:95], v[54:57], v[34:49]
	v_subrev_f32_e32 v106, 2.0, v222
	v_cndmask_b32_e32 v90, v203, v105, vcc
	v_mul_f32_e64 v88, v86, |v89|
	v_cmp_le_f32_e64 vcc, |v89|, s19
	v_subrev_f32_e32 v107, 0x40400000, v222
	v_mul_f32_e64 v91, v86, |v106|
	v_cndmask_b32_e32 v92, v203, v88, vcc
	v_mfma_f32_32x32x16_bf16 v[34:49], v[96:99], v[58:61], v[34:49]
	v_cmp_le_f32_e64 vcc, |v106|, s19
	v_mul_f32_e64 v93, v86, |v107|
	v_cndmask_b32_e32 v91, v203, v91, vcc
	v_cmp_le_f32_e64 vcc, |v107|, s19
	v_subrev_f32_e32 v89, 4.0, v222
	v_mfma_f32_32x32x16_bf16 v[34:49], v[100:103], v[62:65], v[34:49]
	v_cndmask_b32_e32 v88, v203, v93, vcc
	v_mul_f32_e64 v93, v86, |v89|
	v_cmp_le_f32_e64 vcc, |v89|, s19
	s_nop 1
	v_cndmask_b32_e32 v89, v203, v93, vcc
	v_subrev_f32_e32 v93, 0x40a00000, v222
	s_nop 3
	v_fmac_f32_e32 v92, 0x3e38aa3b, v35
	v_mul_f32_e64 v94, v86, |v93|
	v_cmp_le_f32_e64 vcc, |v93|, s19
	v_subrev_f32_e32 v35, 0x40c00000, v222
	v_fmac_f32_e32 v91, 0x3e38aa3b, v36
	v_cndmask_b32_e32 v93, v203, v94, vcc
	v_mul_f32_e64 v36, v86, |v35|
	v_cmp_le_f32_e64 vcc, |v35|, s19
	v_subrev_f32_e32 v35, 0x40e00000, v222
	v_cndmask_b32_e32 v95, v203, v36, vcc
	v_mul_f32_e64 v36, v86, |v35|
	v_cmp_le_f32_e64 vcc, |v35|, s19
	v_subrev_f32_e32 v35, 0x41800000, v222
	v_cndmask_b32_e32 v94, v203, v36, vcc
	v_mul_f32_e64 v36, v86, |v35|
	v_cmp_le_f32_e64 vcc, |v35|, s19
	v_subrev_f32_e32 v35, 0x41880000, v222
	v_cndmask_b32_e32 v97, v203, v36, vcc
	v_mul_f32_e64 v36, v86, |v35|
	v_cmp_le_f32_e64 vcc, |v35|, s19
	v_subrev_f32_e32 v35, 0x41900000, v222
	v_cndmask_b32_e32 v96, v203, v36, vcc
	v_mul_f32_e64 v36, v86, |v35|
	v_cmp_le_f32_e64 vcc, |v35|, s19
	v_subrev_f32_e32 v35, 0x41980000, v222
	v_cndmask_b32_e32 v98, v203, v36, vcc
	v_mul_f32_e64 v36, v86, |v35|
	v_cmp_le_f32_e64 vcc, |v35|, s19
	v_subrev_f32_e32 v35, 0x41a00000, v222
	v_cndmask_b32_e32 v99, v203, v36, vcc
	v_mul_f32_e64 v36, v86, |v35|
	v_cmp_le_f32_e64 vcc, |v35|, s19
	v_fmac_f32_e32 v90, 0x3e38aa3b, v34
	v_subrev_f32_e32 v35, 0x41a80000, v222
	v_fmac_f32_e32 v88, 0x3e38aa3b, v37
	v_max3_f32 v34, v90, s53, v92
	v_cndmask_b32_e32 v100, v203, v36, vcc
	v_mul_f32_e64 v36, v86, |v35|
	v_cmp_le_f32_e64 vcc, |v35|, s19
	v_fmac_f32_e32 v89, 0x3e38aa3b, v38
	v_max3_f32 v34, v34, v91, v88
	v_fmac_f32_e32 v93, 0x3e38aa3b, v39
	v_subrev_f32_e32 v35, 0x41b00000, v222
	v_max3_f32 v34, v34, v89, v93
	v_fmac_f32_e32 v95, 0x3e38aa3b, v40
	v_fmac_f32_e32 v94, 0x3e38aa3b, v41
	v_cndmask_b32_e32 v101, v203, v36, vcc
	v_mul_f32_e64 v36, v86, |v35|
	v_cmp_le_f32_e64 vcc, |v35|, s19
	v_max3_f32 v34, v34, v95, v94
	v_fmac_f32_e32 v97, 0x3e38aa3b, v42
	v_fmac_f32_e32 v96, 0x3e38aa3b, v43
	v_subrev_f32_e32 v35, 0x41b80000, v222
	v_max3_f32 v34, v34, v97, v96
	v_fmac_f32_e32 v98, 0x3e38aa3b, v44
	v_fmac_f32_e32 v99, 0x3e38aa3b, v45
	v_cndmask_b32_e32 v102, v203, v36, vcc
	v_mul_f32_e64 v36, v86, |v35|
	v_cmp_le_f32_e64 vcc, |v35|, s19
	v_max3_f32 v34, v34, v98, v99
	v_fmac_f32_e32 v100, 0x3e38aa3b, v46
	v_fmac_f32_e32 v101, 0x3e38aa3b, v47
	v_cndmask_b32_e32 v87, v203, v36, vcc
	v_max3_f32 v34, v34, v100, v101
	v_fmac_f32_e32 v102, 0x3e38aa3b, v48
	v_fmac_f32_e32 v87, 0x3e38aa3b, v49
	v_max3_f32 v103, v34, v102, v87
	v_mov_b32_e32 v105, v103
	ds_read_b128 v[46:49], v104 offset:4096
	ds_read_b128 v[38:41], v104 offset:5120
	ds_read_b128 v[42:45], v104 offset:6144
	ds_read_b128 v[34:37], v104 offset:7168
	v_permlane32_swap_b32_e32 v105, v103
	v_max_f32_e32 v104, v105, v105
	v_max_f32_e32 v103, v103, v104
	v_cmp_gt_f32_e32 vcc, v103, v82
	s_cbranch_vccz .LBB0_413
	v_max_f32_e32 v103, v103, v103
	v_max_f32_e32 v104, v82, v82
	v_max_f32_e32 v103, v104, v103
	v_sub_f32_e32 v82, v82, v103
	v_exp_f32_e32 v82, v82
	s_nop 0
	v_pk_mul_f32 v[16:17], v[16:17], v[82:83] op_sel_hi:[1,0]
	v_pk_mul_f32 v[14:15], v[14:15], v[82:83] op_sel_hi:[1,0]
	v_pk_mul_f32 v[12:13], v[12:13], v[82:83] op_sel_hi:[1,0]
	v_pk_mul_f32 v[10:11], v[10:11], v[82:83] op_sel_hi:[1,0]
	v_pk_mul_f32 v[8:9], v[8:9], v[82:83] op_sel_hi:[1,0]
	v_pk_mul_f32 v[6:7], v[6:7], v[82:83] op_sel_hi:[1,0]
	v_pk_mul_f32 v[4:5], v[4:5], v[82:83] op_sel_hi:[1,0]
	v_pk_mul_f32 v[2:3], v[2:3], v[82:83] op_sel_hi:[1,0]
	v_pk_mul_f32 v[32:33], v[32:33], v[82:83] op_sel_hi:[1,0]
	v_pk_mul_f32 v[30:31], v[30:31], v[82:83] op_sel_hi:[1,0]
	v_pk_mul_f32 v[28:29], v[28:29], v[82:83] op_sel_hi:[1,0]
	v_pk_mul_f32 v[26:27], v[26:27], v[82:83] op_sel_hi:[1,0]
	v_pk_mul_f32 v[24:25], v[24:25], v[82:83] op_sel_hi:[1,0]
	v_pk_mul_f32 v[22:23], v[22:23], v[82:83] op_sel_hi:[1,0]
	v_pk_mul_f32 v[20:21], v[20:21], v[82:83] op_sel_hi:[1,0]
	v_pk_mul_f32 v[18:19], v[18:19], v[82:83] op_sel_hi:[1,0]
	v_mul_f32_e32 v83, v83, v82
	v_mov_b32_e32 v82, v103

; __device__ __forceinline__ float shx(float v, int mask, int lane) { return __builtin_bit_cast(float, __builtin_amdgcn_ds_bpermute((lane ^ mask) << 2, __builtin_bit_cast(int, v))); }
; template <class BiasF> ...
;     ...
;             const float ktf = (float)(kt + 8 * hi);
;             float tmax = -3.0e38f;
; #pragma unroll
;             for (int r = 0; r < 16; ++r) { sc[r] = sc[r] * c2 + bias.at(r32, kt, ktf + (float)(16 * (r >> 3) + 4 * ((r >> 2) & 1) + (r & 3)), r); tmax = fmaxf(tmax, sc[r]); }
;             tmax = fmaxf(tmax, shx(tmax, 32, lane));
;             if (__any(tmax > m)) { const float mn = fmaxf(m, tmax); const float alpha = __builtin_amdgcn_exp2f(m - mn); m = mn; l *= alpha;
; #pragma unroll
;                 for (int i2 = 0; i2 < 2; ++i2)
; #pragma unroll
;                     for (int r = 0; r < 16; ++r) o[i2][r] *= alpha; }
.LBB0_676:
	s_cmp_lt_i32 s10, s27
	s_cselect_b64 s[6:7], -1, 0
	s_cmp_ge_u32 s10, s28
	s_cselect_b64 s[30:31], -1, 0
	s_or_b64 s[6:7], s[6:7], s[30:31]
	s_and_b64 vcc, exec, s[6:7]
	s_cbranch_vccnz .LBB0_680
	v_lshl_add_u32 v100, s26, 13, v79
	ds_read_b128 v[34:37], v100
	v_add_u32_e32 v38, s10, v66
	v_cvt_f32_i32_e32 v84, v38
	v_sub_f32_e32 v222, v81, v84
	ds_read_b128 v[88:91], v100 offset:1024
	ds_read_b128 v[92:95], v100 offset:2048
	ds_read_b128 v[96:99], v100 offset:3072
	s_waitcnt lgkmcnt(0)
	v_mfma_f32_32x32x16_bf16 v[34:49], v[34:37], v[50:53], 0
	v_sub_f32_e32 v85, v81, v84
	v_mul_f32_e64 v102, v82, |v85|
	v_subrev_f32_e32 v86, 1.0, v222
	v_cmp_le_f32_e64 vcc, |v85|, s33
	v_mfma_f32_32x32x16_bf16 v[34:49], v[88:91], v[54:57], v[34:49]
	v_subrev_f32_e32 v103, 2.0, v222
	v_cndmask_b32_e32 v87, v203, v102, vcc
	v_mul_f32_e64 v85, v82, |v86|
	v_cmp_le_f32_e64 vcc, |v86|, s33
	v_subrev_f32_e32 v101, 0x40400000, v222
	v_mul_f32_e64 v88, v82, |v103|
	v_cndmask_b32_e32 v89, v203, v85, vcc
	v_mfma_f32_32x32x16_bf16 v[34:49], v[92:95], v[58:61], v[34:49]
	v_cmp_le_f32_e64 vcc, |v103|, s33
	v_mul_f32_e64 v90, v82, |v101|
	v_cndmask_b32_e32 v88, v203, v88, vcc
	v_cmp_le_f32_e64 vcc, |v101|, s33
	v_subrev_f32_e32 v86, 4.0, v222
	v_mfma_f32_32x32x16_bf16 v[34:49], v[96:99], v[62:65], v[34:49]
	v_cndmask_b32_e32 v85, v203, v90, vcc
	v_mul_f32_e64 v90, v82, |v86|
	v_cmp_le_f32_e64 vcc, |v86|, s33
	s_nop 1
	v_cndmask_b32_e32 v86, v203, v90, vcc
	v_subrev_f32_e32 v90, 0x40a00000, v222
	s_nop 3
	v_fmac_f32_e32 v89, 0x3e38aa3b, v35
	v_mul_f32_e64 v91, v82, |v90|
	v_cmp_le_f32_e64 vcc, |v90|, s33
	v_subrev_f32_e32 v35, 0x40c00000, v222
	v_fmac_f32_e32 v88, 0x3e38aa3b, v36
	v_cndmask_b32_e32 v90, v203, v91, vcc
	v_mul_f32_e64 v36, v82, |v35|
	v_cmp_le_f32_e64 vcc, |v35|, s33
	v_subrev_f32_e32 v35, 0x40e00000, v222
	v_cndmask_b32_e32 v92, v203, v36, vcc
	v_mul_f32_e64 v36, v82, |v35|
	v_cmp_le_f32_e64 vcc, |v35|, s33
	v_subrev_f32_e32 v35, 0x41800000, v222
	v_cndmask_b32_e32 v91, v203, v36, vcc
	v_mul_f32_e64 v36, v82, |v35|
	v_cmp_le_f32_e64 vcc, |v35|, s33
	v_subrev_f32_e32 v35, 0x41880000, v222
	v_cndmask_b32_e32 v94, v203, v36, vcc
	v_mul_f32_e64 v36, v82, |v35|
	v_cmp_le_f32_e64 vcc, |v35|, s33
	v_subrev_f32_e32 v35, 0x41900000, v222
	v_cndmask_b32_e32 v93, v203, v36, vcc
	v_mul_f32_e64 v36, v82, |v35|
	v_cmp_le_f32_e64 vcc, |v35|, s33
	v_subrev_f32_e32 v35, 0x41980000, v222
	v_cndmask_b32_e32 v95, v203, v36, vcc
	v_mul_f32_e64 v36, v82, |v35|
	v_cmp_le_f32_e64 vcc, |v35|, s33
	v_subrev_f32_e32 v35, 0x41a00000, v222
	v_cndmask_b32_e32 v96, v203, v36, vcc
	v_mul_f32_e64 v36, v82, |v35|
	v_cmp_le_f32_e64 vcc, |v35|, s33
	v_fmac_f32_e32 v87, 0x3e38aa3b, v34
	v_subrev_f32_e32 v35, 0x41a80000, v222
	v_fmac_f32_e32 v85, 0x3e38aa3b, v37
	v_max3_f32 v34, v87, s53, v89
	v_cndmask_b32_e32 v97, v203, v36, vcc
	v_mul_f32_e64 v36, v82, |v35|
	v_cmp_le_f32_e64 vcc, |v35|, s33
	v_fmac_f32_e32 v86, 0x3e38aa3b, v38
	v_max3_f32 v34, v34, v88, v85
	v_fmac_f32_e32 v90, 0x3e38aa3b, v39
	v_subrev_f32_e32 v35, 0x41b00000, v222
	v_max3_f32 v34, v34, v86, v90
	v_fmac_f32_e32 v92, 0x3e38aa3b, v40
	v_fmac_f32_e32 v91, 0x3e38aa3b, v41
	v_cndmask_b32_e32 v98, v203, v36, vcc
	v_mul_f32_e64 v36, v82, |v35|
	v_cmp_le_f32_e64 vcc, |v35|, s33
	v_max3_f32 v34, v34, v92, v91
	v_fmac_f32_e32 v94, 0x3e38aa3b, v42
	v_fmac_f32_e32 v93, 0x3e38aa3b, v43
	v_subrev_f32_e32 v35, 0x41b80000, v222
	v_max3_f32 v34, v34, v94, v93
	v_fmac_f32_e32 v95, 0x3e38aa3b, v44
	v_fmac_f32_e32 v96, 0x3e38aa3b, v45
	v_cndmask_b32_e32 v99, v203, v36, vcc
	v_mul_f32_e64 v36, v82, |v35|
	v_cmp_le_f32_e64 vcc, |v35|, s33
	v_max3_f32 v34, v34, v95, v96
	v_fmac_f32_e32 v97, 0x3e38aa3b, v46
	v_fmac_f32_e32 v98, 0x3e38aa3b, v47
	v_cndmask_b32_e32 v84, v203, v36, vcc
	v_max3_f32 v34, v34, v97, v98
	v_fmac_f32_e32 v99, 0x3e38aa3b, v48
	v_fmac_f32_e32 v84, 0x3e38aa3b, v49
	v_max3_f32 v101, v34, v99, v84
	v_mov_b32_e32 v102, v101
	ds_read_b128 v[46:49], v100 offset:4096
	ds_read_b128 v[38:41], v100 offset:5120
	ds_read_b128 v[42:45], v100 offset:6144
	ds_read_b128 v[34:37], v100 offset:7168
	v_permlane32_swap_b32_e32 v102, v101
	v_max_f32_e32 v100, v102, v102
	v_max_f32_e32 v100, v101, v100
	v_cmp_gt_f32_e32 vcc, v100, v83
	s_cbranch_vccz .LBB0_679
	v_max_f32_e32 v100, v100, v100
	v_max_f32_e32 v101, v83, v83
	v_max_f32_e32 v101, v101, v100
	v_sub_f32_e32 v83, v83, v101
	v_exp_f32_e32 v100, v83
	v_mov_b32_e32 v83, v101
	v_pk_mul_f32 v[16:17], v[16:17], v[100:101] op_sel_hi:[1,0]
	v_pk_mul_f32 v[14:15], v[14:15], v[100:101] op_sel_hi:[1,0]
	v_pk_mul_f32 v[12:13], v[12:13], v[100:101] op_sel_hi:[1,0]
	v_pk_mul_f32 v[10:11], v[10:11], v[100:101] op_sel_hi:[1,0]
	v_pk_mul_f32 v[8:9], v[8:9], v[100:101] op_sel_hi:[1,0]
	v_pk_mul_f32 v[6:7], v[6:7], v[100:101] op_sel_hi:[1,0]
	v_pk_mul_f32 v[4:5], v[4:5], v[100:101] op_sel_hi:[1,0]
	v_pk_mul_f32 v[2:3], v[2:3], v[100:101] op_sel_hi:[1,0]
	v_pk_mul_f32 v[32:33], v[32:33], v[100:101] op_sel_hi:[1,0]
	v_pk_mul_f32 v[30:31], v[30:31], v[100:101] op_sel_hi:[1,0]
	v_pk_mul_f32 v[28:29], v[28:29], v[100:101] op_sel_hi:[1,0]
	v_pk_mul_f32 v[26:27], v[26:27], v[100:101] op_sel_hi:[1,0]
	v_pk_mul_f32 v[24:25], v[24:25], v[100:101] op_sel_hi:[1,0]
	v_pk_mul_f32 v[22:23], v[22:23], v[100:101] op_sel_hi:[1,0]
	v_pk_mul_f32 v[20:21], v[20:21], v[100:101] op_sel_hi:[1,0]
	v_pk_mul_f32 v[18:19], v[18:19], v[100:101] op_sel_hi:[1,0]
	v_mul_f32_e32 v80, v80, v100
